# v26 plus the five wait states after the off-diagonal QK MFMAs carry the no-rescale defaults instead of s_nop 4
# baseline (speedup 1.0000x reference)
; __device__ __forceinline__ void attn_unit(const Params& P, int li, LAS unsigned char* lds, int b, int h, int qb, float lam, float one_m_li) {
;     ...
;             const LAS unsigned char* kp = cb + mp * 8192 + r32 * 128;
;             bf16x8 kf[8];
; #pragma unroll
;             for (int d0 = 0; d0 < 4; ++d0) { kf[2 * d0] = *(const LAS bf16x8*)(kp + coff[d0]); kf[2 * d0 + 1] = *(const LAS bf16x8*)(kp + 4096 + coff[d0]); }
;             const bool diag = (t == cw);
;             if (diag) { p0 = f32x16{}; p1 = f32x16{}; }
;             else {
;                 const float nc0 = -(sl * ((float)((cw - t) * 64) + qinf) + m), nc1 = fadd_s(nc0, sl32);
;                 float b0[4], b1[4];
;                 b0[0] = nc0; b0[1] = fadd_s(nc0, sl8); b0[2] = fma2_s(sl8, nc0); b0[3] = fadd_s(nc0, sl24);
;                 b1[0] = nc1; b1[1] = fadd_s(nc1, sl8); b1[2] = fma2_s(sl8, nc1); b1[3] = fadd_s(nc1, sl24);
; #pragma unroll
;                 for (int q = 0; q < 4; ++q) {
;                     p0[4 * q] = b0[q]; p0[4 * q + 1] = fadd_s(b0[q], sl); p0[4 * q + 2] = fma2_s(sl, b0[q]); p0[4 * q + 3] = fadd_s(b0[q], sl3);
;                     p1[4 * q] = b1[q]; p1[4 * q + 1] = fadd_s(b1[q], sl); p1[4 * q + 2] = fma2_s(sl, b1[q]); p1[4 * q + 3] = fadd_s(b1[q], sl3);
;                 }
;             }
;             __builtin_amdgcn_sched_barrier(0);
;             __builtin_amdgcn_s_setprio(1);
; #pragma unroll
;             for (int d0 = 0; d0 < 4; ++d0) {
;                 p0 = __builtin_amdgcn_mfma_f32_32x32x16_bf16(kf[2 * d0], qr[d0], p0, 0, 0, 0);
;                 p1 = __builtin_amdgcn_mfma_f32_32x32x16_bf16(kf[2 * d0 + 1], qr[d0], p1, 0, 0, 0);
;             }
;             __builtin_amdgcn_s_setprio(0);
;             if (diag) {
;                 float qf = qinf; asm volatile("" : "+v"(qf));
; #pragma unroll
;                 for (int r = 0; r < 16; ++r) { const float d0 = qf - (float)crow(r, 0);
;                     p0[r] = fmaf(-sl, fabsf(d0), p0[r]); p1[r] = fmaf(-sl, fabsf(d0 - 32.f), p1[r]); }
;             }
;             float mx = max3f(p0[0], p1[0], p0[1]);
; #pragma unroll
;             for (int r = 1; r < 15; ++r) mx = max3f(mx, p1[r], p0[r + 1]);
;             mx = max3f(mx, p1[15], mx);
;             const float mt = xor32_max(mx);
;             bool resc; float ra;
;             if (diag) {
;                 resc = true; ra = ex2(m - mt); m = mt;
.Lattn_offdiag:
	s_lshl_b32 s10, s21, 15
	s_and_b32 s22, s10, 0x18000
	v_add_u32_e32 v112, s22, v227
	v_add_u32_e32 v113, v112, v225
	ds_read_b128 v[76:79], v113
	ds_read_b128 v[68:71], v113 offset:4096
	v_add_u32_e32 v113, v112, v224
	ds_read_b128 v[72:75], v113
	ds_read_b128 v[92:95], v113 offset:4096
	v_add_u32_e32 v113, v112, v223
	v_add_u32_e32 v112, v112, v221
	ds_read_b128 v[64:67], v113
	ds_read_b128 v[84:87], v113 offset:4096
	ds_read_b128 v[88:91], v112
	ds_read_b128 v[80:83], v112 offset:4096
	s_sub_i32 s4, s31, s4
	s_lshl_b32 s4, s4, 6
	v_cvt_f32_i32_e32 v112, s4
	v_add_f32_e32 v112, v220, v112
	v_fma_f32 v112, v197, v112, v232
	v_xor_b32_e32 v96, 0x80000000, v112
	v_add_f32_e32 v112, v96, v201
	v_add_f32_e32 v100, v96, v199
	v_fma_f32 v104, v199, 2.0, v96
	v_add_f32_e32 v108, v96, v200
	v_add_f32_e32 v97, v96, v197
	v_fma_f32 v98, v197, 2.0, v96
	v_add_f32_e32 v99, v96, v198
	v_add_f32_e32 v101, v100, v197
	v_fma_f32 v102, v197, 2.0, v100
	v_add_f32_e32 v103, v100, v198
	v_add_f32_e32 v105, v104, v197
	v_fma_f32 v106, v197, 2.0, v104
	v_add_f32_e32 v107, v104, v198
	v_add_f32_e32 v109, v108, v197
	v_fma_f32 v110, v197, 2.0, v108
	v_add_f32_e32 v111, v108, v198
	s_setprio 1
	s_waitcnt lgkmcnt(0)
	v_mfma_f32_32x32x16_bf16 v[96:111], v[76:79], v[128:131], v[96:111]
	v_add_f32_e32 v116, v112, v199
	v_fma_f32 v120, v199, 2.0, v112
	v_add_f32_e32 v124, v112, v200
	v_add_f32_e32 v113, v112, v197
	v_fma_f32 v114, v197, 2.0, v112
	v_mfma_f32_32x32x16_bf16 v[96:111], v[72:75], v[132:135], v[96:111]
	v_add_f32_e32 v115, v112, v198
	v_add_f32_e32 v117, v116, v197
	v_fma_f32 v118, v197, 2.0, v116
	v_add_f32_e32 v119, v116, v198
	v_add_f32_e32 v121, v120, v197
	v_mfma_f32_32x32x16_bf16 v[96:111], v[64:67], v[136:139], v[96:111]
	v_fma_f32 v122, v197, 2.0, v120
	v_add_f32_e32 v123, v120, v198
	v_add_f32_e32 v125, v124, v197
	v_fma_f32 v126, v197, 2.0, v124
	v_add_f32_e32 v127, v124, v198
	v_mfma_f32_32x32x16_bf16 v[96:111], v[88:91], v[140:143], v[96:111]
	s_nop 0
	v_mfma_f32_32x32x16_bf16 v[112:127], v[68:71], v[128:131], v[112:127]
	v_mfma_f32_32x32x16_bf16 v[112:127], v[92:95], v[132:135], v[112:127]
	v_mfma_f32_32x32x16_bf16 v[112:127], v[84:87], v[136:139], v[112:127]
	v_mfma_f32_32x32x16_bf16 v[112:127], v[80:83], v[140:143], v[112:127]
	s_setprio 0
	v_mov_b32_e32 v192, 1.0
	v_mov_b32_e32 v187, v232
	s_mov_b32 s4, 0x41000000
	s_nop 1
	v_max3_f32 v80, v96, v97, v98
	v_max3_f32 v80, v80, v99, v100
	v_max3_f32 v80, v80, v101, v102
	v_max3_f32 v80, v80, v103, v104
	v_max3_f32 v80, v80, v105, v106
	v_max3_f32 v80, v80, v107, v108
	v_max3_f32 v80, v80, v109, v110
	v_max3_f32 v80, v80, v111, v112
	v_max3_f32 v80, v80, v113, v114
	v_max3_f32 v80, v80, v115, v116
	v_max3_f32 v80, v80, v117, v118
	v_max3_f32 v80, v80, v119, v120
	v_max3_f32 v80, v80, v121, v122
	v_max3_f32 v80, v80, v123, v124
	v_max3_f32 v80, v80, v125, v126
	v_max3_f32 v80, v80, v127, v80
	s_nop 0
	v_mov_b32_e32 v81, v80
	s_nop 1
	v_permlane32_swap_b32_e32 v80, v81
	v_max_f32_e32 v233, v80, v81
	v_cmp_lt_f32_e32 vcc, s4, v233
	s_mov_b64 s[22:23], 0
	s_cbranch_vccnz .Lattn_od_resc
	s_mov_b64 s[42:43], 0
